# v025
# baseline (speedup 1.0000x reference)
.Lmy_rs_join:
	v_lshl_add_u64 v[148:149], s[22:23], 0, v[148:149]
	s_waitcnt lgkmcnt(3)
	v_cndmask_b32_e64 v161, v166, v156, s[42:43]
	s_waitcnt lgkmcnt(2)
	v_cndmask_b32_e64 v162, v167, v163, s[42:43]
	v_cndmask_b32_e64 v146, v162, v161, s[40:41]
	v_lshlrev_b32_e32 v0, 1, v138
	v_pk_mul_f32 v[128:129], v[128:129], v[146:147] op_sel_hi:[1,0]
	v_pk_mul_f32 v[126:127], v[126:127], v[146:147] op_sel_hi:[1,0]
	v_pk_mul_f32 v[124:125], v[124:125], v[146:147] op_sel_hi:[1,0]
	v_pk_mul_f32 v[122:123], v[122:123], v[146:147] op_sel_hi:[1,0]
	v_cndmask_b32_e64 v147, 0, 1, s[50:51]
	v_lshl_add_u64 v[148:149], v[148:149], 0, v[0:1]
	v_cvt_pk_bf16_f32 v168, v126, v127
	v_cvt_pk_bf16_f32 v169, v128, v129
	v_cvt_pk_bf16_f32 v170, v122, v123
	v_cvt_pk_bf16_f32 v171, v124, v125
	v_cmp_ne_u32_e64 s[48:49], 1, v147
	s_andn2_b64 vcc, exec, s[50:51]
	v_cmp_lt_i32_e64 s[50:51], v157, v154
	global_store_dwordx4 v[148:149], v[168:171], off nt
	s_cbranch_vccnz .LBB0_188
	v_pk_mul_f32 v[128:129], v[128:129], v[128:129]
	v_pk_mul_f32 v[126:127], v[126:127], v[126:127]
	v_pk_mul_f32 v[124:125], v[124:125], v[124:125]
	v_pk_mov_b32 v[168:169], v[126:127], v[128:129] op_sel:[1,0]
	v_mov_b32_e32 v127, v129
	v_pk_mul_f32 v[122:123], v[122:123], v[122:123]
	v_pk_add_f32 v[126:127], v[168:169], v[126:127]
	v_mov_b32_e32 v128, v124
	v_mov_b32_e32 v129, v122
	v_mov_b32_e32 v122, v125
	v_pk_add_f32 v[122:123], v[128:129], v[122:123]
	v_add_f32_e32 v124, v126, v127
	v_add_f32_e32 v123, v123, v124
	v_add_f32_e32 v122, v122, v123
	ds_bpermute_b32 v123, v155, v122
	s_waitcnt lgkmcnt(0)
	v_add_f32_e32 v122, v122, v123
	v_cndmask_b32_e64 v123, v229, v157, s[50:51]
	v_lshlrev_b32_e32 v123, 2, v123
	ds_bpermute_b32 v123, v123, v122
	s_waitcnt lgkmcnt(0)
	v_add_f32_e32 v122, v122, v123
	v_max_f32_e32 v159, 0, v122
.LBB0_188:
	v_mov_b32_e32 v147, v146
	v_mov_b32_e32 v122, v146
	v_mov_b32_e32 v123, v146
	v_add_co_u32_e32 v126, vcc, 0x600000, v148
	v_pk_mul_f32 v[120:121], v[120:121], v[122:123]
	v_pk_mul_f32 v[118:119], v[118:119], v[146:147]
	v_pk_mul_f32 v[116:117], v[116:117], v[122:123]
	v_pk_mul_f32 v[114:115], v[114:115], v[146:147]
	v_addc_co_u32_e32 v127, vcc, 0, v149, vcc
	v_cvt_pk_bf16_f32 v122, v118, v119
	v_cvt_pk_bf16_f32 v123, v120, v121
	v_cvt_pk_bf16_f32 v124, v114, v115
	v_cvt_pk_bf16_f32 v125, v116, v117
	s_and_b64 vcc, exec, s[48:49]
	global_store_dwordx4 v[126:127], v[122:125], off nt
	s_cbranch_vccnz .LBB0_190
	v_pk_mul_f32 v[120:121], v[120:121], v[120:121]
	v_pk_mul_f32 v[118:119], v[118:119], v[118:119]
	v_pk_mul_f32 v[116:117], v[116:117], v[116:117]
	v_pk_mov_b32 v[122:123], v[118:119], v[120:121] op_sel:[1,0]
	v_mov_b32_e32 v119, v121
	v_pk_mul_f32 v[114:115], v[114:115], v[114:115]
	v_pk_add_f32 v[118:119], v[122:123], v[118:119]
	v_mov_b32_e32 v120, v116
	v_mov_b32_e32 v121, v114
	v_mov_b32_e32 v114, v117
	v_pk_add_f32 v[114:115], v[120:121], v[114:115]
	v_add_f32_e32 v116, v118, v119
	v_add_f32_e32 v115, v115, v116
	v_add_f32_e32 v114, v114, v115
	ds_bpermute_b32 v115, v155, v114
	v_cmp_lt_i32_e32 vcc, v157, v154
	s_waitcnt lgkmcnt(0)
	v_add_f32_e32 v114, v114, v115
	v_cndmask_b32_e32 v115, v229, v157, vcc
	v_lshlrev_b32_e32 v115, 2, v115
	ds_bpermute_b32 v115, v115, v114
	s_waitcnt lgkmcnt(0)
	v_add_f32_e32 v114, v114, v115
	v_max_f32_e32 v153, 0, v114
.LBB0_190:
	v_or_b32_e32 v114, 16, v144
	s_waitcnt lgkmcnt(0)
	v_cndmask_b32_e64 v118, v165, v160, s[42:43]
	v_cndmask_b32_e64 v119, v164, v158, s[42:43]
	v_ashrrev_i32_e32 v115, 31, v114
	v_cndmask_b32_e64 v116, v118, v119, s[40:41]
	v_lshlrev_b64 v[114:115], 8, v[114:115]
	v_lshl_add_u64 v[114:115], s[22:23], 0, v[114:115]
	v_pk_mul_f32 v[112:113], v[112:113], v[116:117] op_sel_hi:[1,0]
	v_pk_mul_f32 v[110:111], v[110:111], v[116:117] op_sel_hi:[1,0]
	v_pk_mul_f32 v[108:109], v[108:109], v[116:117] op_sel_hi:[1,0]
	v_pk_mul_f32 v[106:107], v[106:107], v[116:117] op_sel_hi:[1,0]
	v_lshl_add_u64 v[114:115], v[114:115], 0, v[0:1]
	v_cvt_pk_bf16_f32 v120, v110, v111
	v_cvt_pk_bf16_f32 v121, v112, v113
	v_cvt_pk_bf16_f32 v122, v106, v107
	v_cvt_pk_bf16_f32 v123, v108, v109
	s_and_b64 vcc, exec, s[48:49]
	global_store_dwordx4 v[114:115], v[120:123], off nt
	s_cbranch_vccnz .LBB0_192
	v_pk_mul_f32 v[112:113], v[112:113], v[112:113]
	v_pk_mul_f32 v[110:111], v[110:111], v[110:111]
	v_pk_mul_f32 v[108:109], v[108:109], v[108:109]
	v_pk_mov_b32 v[120:121], v[110:111], v[112:113] op_sel:[1,0]
	v_mov_b32_e32 v111, v113
	v_pk_mul_f32 v[106:107], v[106:107], v[106:107]
	v_pk_add_f32 v[110:111], v[120:121], v[110:111]
	v_mov_b32_e32 v112, v108
	v_mov_b32_e32 v113, v106
	v_mov_b32_e32 v106, v109
	v_pk_add_f32 v[106:107], v[112:113], v[106:107]
	v_add_f32_e32 v108, v110, v111
	v_add_f32_e32 v107, v107, v108
	v_add_f32_e32 v106, v106, v107
	ds_bpermute_b32 v107, v155, v106
	v_cmp_lt_i32_e32 vcc, v157, v154
	s_waitcnt lgkmcnt(0)
	v_add_f32_e32 v106, v106, v107
	v_cndmask_b32_e32 v107, v229, v157, vcc
	v_lshlrev_b32_e32 v107, 2, v107
	ds_bpermute_b32 v107, v107, v106
	s_waitcnt lgkmcnt(0)
	v_add_f32_e32 v106, v106, v107
	v_max_f32_e32 v107, v159, v159
	v_max_f32_e32 v159, v107, v106
.LBB0_192:
	v_mov_b32_e32 v117, v116
	v_mov_b32_e32 v106, v116
	v_mov_b32_e32 v107, v116
	v_add_co_u32_e32 v110, vcc, 0x600000, v114
	v_pk_mul_f32 v[104:105], v[104:105], v[106:107]
	v_pk_mul_f32 v[102:103], v[102:103], v[116:117]
	v_pk_mul_f32 v[100:101], v[100:101], v[106:107]
	v_pk_mul_f32 v[98:99], v[98:99], v[116:117]
	v_addc_co_u32_e32 v111, vcc, 0, v115, vcc
	v_cvt_pk_bf16_f32 v106, v102, v103
	v_cvt_pk_bf16_f32 v107, v104, v105
	v_cvt_pk_bf16_f32 v108, v98, v99
	v_cvt_pk_bf16_f32 v109, v100, v101
	s_and_b64 vcc, exec, s[48:49]
	global_store_dwordx4 v[110:111], v[106:109], off nt
	s_cbranch_vccnz .LBB0_194
	v_pk_mul_f32 v[104:105], v[104:105], v[104:105]
	v_pk_mul_f32 v[102:103], v[102:103], v[102:103]
	v_pk_mul_f32 v[100:101], v[100:101], v[100:101]
	v_pk_mov_b32 v[106:107], v[102:103], v[104:105] op_sel:[1,0]
	v_mov_b32_e32 v103, v105
	v_pk_mul_f32 v[98:99], v[98:99], v[98:99]
	v_pk_add_f32 v[102:103], v[106:107], v[102:103]
	v_mov_b32_e32 v104, v100
	v_mov_b32_e32 v105, v98
	v_mov_b32_e32 v98, v101
	v_pk_add_f32 v[98:99], v[104:105], v[98:99]
	v_add_f32_e32 v100, v102, v103
	v_add_f32_e32 v99, v99, v100
	v_add_f32_e32 v98, v98, v99
	ds_bpermute_b32 v99, v155, v98
	v_cmp_lt_i32_e32 vcc, v157, v154
	s_waitcnt lgkmcnt(0)
	v_add_f32_e32 v98, v98, v99
	v_cndmask_b32_e32 v99, v229, v157, vcc
	v_lshlrev_b32_e32 v99, 2, v99
	ds_bpermute_b32 v99, v99, v98
	s_waitcnt lgkmcnt(0)
	v_add_f32_e32 v98, v98, v99
	v_max_f32_e32 v99, v153, v153
	v_max_f32_e32 v153, v99, v98
.LBB0_194:
	v_or_b32_e32 v98, 32, v144
	v_cndmask_b32_e64 v102, v163, v167, s[42:43]
	v_cndmask_b32_e64 v103, v156, v166, s[42:43]
	v_ashrrev_i32_e32 v99, 31, v98
	v_cndmask_b32_e64 v100, v102, v103, s[40:41]
	v_lshlrev_b64 v[98:99], 8, v[98:99]
	v_lshl_add_u64 v[98:99], s[22:23], 0, v[98:99]
	v_pk_mul_f32 v[96:97], v[96:97], v[100:101] op_sel_hi:[1,0]
	v_pk_mul_f32 v[94:95], v[94:95], v[100:101] op_sel_hi:[1,0]
	v_pk_mul_f32 v[92:93], v[92:93], v[100:101] op_sel_hi:[1,0]
	v_pk_mul_f32 v[90:91], v[90:91], v[100:101] op_sel_hi:[1,0]
	v_lshl_add_u64 v[98:99], v[98:99], 0, v[0:1]
	v_cvt_pk_bf16_f32 v104, v94, v95
	v_cvt_pk_bf16_f32 v105, v96, v97
	v_cvt_pk_bf16_f32 v106, v90, v91
	v_cvt_pk_bf16_f32 v107, v92, v93
	s_and_b64 vcc, exec, s[48:49]
	global_store_dwordx4 v[98:99], v[104:107], off nt
	s_cbranch_vccnz .LBB0_196
	v_pk_mul_f32 v[96:97], v[96:97], v[96:97]
	v_pk_mul_f32 v[94:95], v[94:95], v[94:95]
	v_pk_mul_f32 v[92:93], v[92:93], v[92:93]
	v_pk_mov_b32 v[104:105], v[94:95], v[96:97] op_sel:[1,0]
	v_mov_b32_e32 v95, v97
	v_pk_mul_f32 v[90:91], v[90:91], v[90:91]
	v_pk_add_f32 v[94:95], v[104:105], v[94:95]
	v_mov_b32_e32 v96, v92
	v_mov_b32_e32 v97, v90
	v_mov_b32_e32 v90, v93
	v_pk_add_f32 v[90:91], v[96:97], v[90:91]
	v_add_f32_e32 v92, v94, v95
	v_add_f32_e32 v91, v91, v92
	v_add_f32_e32 v90, v90, v91
	ds_bpermute_b32 v91, v155, v90
	v_cmp_lt_i32_e32 vcc, v157, v154
	s_waitcnt lgkmcnt(0)
	v_add_f32_e32 v90, v90, v91
	v_cndmask_b32_e32 v91, v229, v157, vcc
	v_lshlrev_b32_e32 v91, 2, v91
	ds_bpermute_b32 v91, v91, v90
	s_waitcnt lgkmcnt(0)
	v_add_f32_e32 v90, v90, v91
	v_max_f32_e32 v91, v159, v159
	v_max_f32_e32 v159, v91, v90
.LBB0_196:
	v_mov_b32_e32 v101, v100
	v_mov_b32_e32 v90, v100
	v_mov_b32_e32 v91, v100
	v_add_co_u32_e32 v94, vcc, 0x600000, v98
	v_pk_mul_f32 v[88:89], v[88:89], v[90:91]
	v_pk_mul_f32 v[86:87], v[86:87], v[100:101]
	v_pk_mul_f32 v[84:85], v[84:85], v[90:91]
	v_pk_mul_f32 v[82:83], v[82:83], v[100:101]
	v_addc_co_u32_e32 v95, vcc, 0, v99, vcc
	v_cvt_pk_bf16_f32 v90, v86, v87
	v_cvt_pk_bf16_f32 v91, v88, v89
	v_cvt_pk_bf16_f32 v92, v82, v83
	v_cvt_pk_bf16_f32 v93, v84, v85
	s_and_b64 vcc, exec, s[48:49]
	global_store_dwordx4 v[94:95], v[90:93], off nt
	s_cbranch_vccnz .LBB0_198
	v_pk_mul_f32 v[88:89], v[88:89], v[88:89]
	v_pk_mul_f32 v[86:87], v[86:87], v[86:87]
	v_pk_mul_f32 v[84:85], v[84:85], v[84:85]
	v_pk_mov_b32 v[90:91], v[86:87], v[88:89] op_sel:[1,0]
	v_mov_b32_e32 v87, v89
	v_pk_mul_f32 v[82:83], v[82:83], v[82:83]
	v_pk_add_f32 v[86:87], v[90:91], v[86:87]
	v_mov_b32_e32 v88, v84
	v_mov_b32_e32 v89, v82
	v_mov_b32_e32 v82, v85
	v_pk_add_f32 v[82:83], v[88:89], v[82:83]
	v_add_f32_e32 v84, v86, v87
	v_add_f32_e32 v83, v83, v84
	v_add_f32_e32 v82, v82, v83
	ds_bpermute_b32 v83, v155, v82
	v_cmp_lt_i32_e32 vcc, v157, v154
	s_waitcnt lgkmcnt(0)
	v_add_f32_e32 v82, v82, v83
	v_cndmask_b32_e32 v83, v229, v157, vcc
	v_lshlrev_b32_e32 v83, 2, v83
	ds_bpermute_b32 v83, v83, v82
	s_waitcnt lgkmcnt(0)
	v_add_f32_e32 v82, v82, v83
	v_max_f32_e32 v83, v153, v153
	v_max_f32_e32 v153, v83, v82
.LBB0_198:
	v_or_b32_e32 v82, 48, v144
	v_cndmask_b32_e64 v86, v160, v165, s[42:43]
	v_cndmask_b32_e64 v87, v158, v164, s[42:43]
	v_ashrrev_i32_e32 v83, 31, v82
	v_cndmask_b32_e64 v84, v86, v87, s[40:41]
	v_lshlrev_b64 v[82:83], 8, v[82:83]
	v_lshl_add_u64 v[82:83], s[22:23], 0, v[82:83]
	v_pk_mul_f32 v[80:81], v[80:81], v[84:85] op_sel_hi:[1,0]
	v_pk_mul_f32 v[78:79], v[78:79], v[84:85] op_sel_hi:[1,0]
	v_pk_mul_f32 v[76:77], v[76:77], v[84:85] op_sel_hi:[1,0]
	v_pk_mul_f32 v[74:75], v[74:75], v[84:85] op_sel_hi:[1,0]
	v_lshl_add_u64 v[82:83], v[82:83], 0, v[0:1]
	v_cvt_pk_bf16_f32 v88, v78, v79
	v_cvt_pk_bf16_f32 v89, v80, v81
	v_cvt_pk_bf16_f32 v90, v74, v75
	v_cvt_pk_bf16_f32 v91, v76, v77
	s_and_b64 vcc, exec, s[48:49]
	global_store_dwordx4 v[82:83], v[88:91], off nt
	s_cbranch_vccnz .LBB0_200
	v_pk_mul_f32 v[80:81], v[80:81], v[80:81]
	v_pk_mul_f32 v[78:79], v[78:79], v[78:79]
	v_pk_mul_f32 v[76:77], v[76:77], v[76:77]
	v_pk_mov_b32 v[88:89], v[78:79], v[80:81] op_sel:[1,0]
	v_mov_b32_e32 v79, v81
	v_pk_mul_f32 v[74:75], v[74:75], v[74:75]
	v_pk_add_f32 v[78:79], v[88:89], v[78:79]
	v_mov_b32_e32 v80, v76
	v_mov_b32_e32 v81, v74
	v_mov_b32_e32 v74, v77
	v_pk_add_f32 v[74:75], v[80:81], v[74:75]
	v_add_f32_e32 v76, v78, v79
	v_add_f32_e32 v75, v75, v76
	v_add_f32_e32 v74, v74, v75
	ds_bpermute_b32 v75, v155, v74
	v_cmp_lt_i32_e32 vcc, v157, v154
	s_waitcnt lgkmcnt(0)
	v_add_f32_e32 v74, v74, v75
	v_cndmask_b32_e32 v75, v229, v157, vcc
	v_lshlrev_b32_e32 v75, 2, v75
	ds_bpermute_b32 v75, v75, v74
	s_waitcnt lgkmcnt(0)
	v_add_f32_e32 v74, v74, v75
	v_max_f32_e32 v75, v159, v159
	v_max_f32_e32 v159, v75, v74
.LBB0_200:
	v_mov_b32_e32 v85, v84
	v_mov_b32_e32 v74, v84
	v_mov_b32_e32 v75, v84
	v_add_co_u32_e32 v78, vcc, 0x600000, v82
	v_pk_mul_f32 v[72:73], v[72:73], v[74:75]
	v_pk_mul_f32 v[70:71], v[70:71], v[84:85]
	v_pk_mul_f32 v[68:69], v[68:69], v[74:75]
	v_pk_mul_f32 v[66:67], v[66:67], v[84:85]
	v_addc_co_u32_e32 v79, vcc, 0, v83, vcc
	v_cvt_pk_bf16_f32 v74, v70, v71
	v_cvt_pk_bf16_f32 v75, v72, v73
	v_cvt_pk_bf16_f32 v76, v66, v67
	v_cvt_pk_bf16_f32 v77, v68, v69
	s_and_b64 vcc, exec, s[48:49]
	global_store_dwordx4 v[78:79], v[74:77], off nt
	s_cbranch_vccnz .LBB0_202
	v_pk_mul_f32 v[72:73], v[72:73], v[72:73]
	v_pk_mul_f32 v[70:71], v[70:71], v[70:71]
	v_pk_mul_f32 v[68:69], v[68:69], v[68:69]
	v_pk_mov_b32 v[74:75], v[70:71], v[72:73] op_sel:[1,0]
	v_mov_b32_e32 v71, v73
	v_pk_mul_f32 v[66:67], v[66:67], v[66:67]
	v_pk_add_f32 v[70:71], v[74:75], v[70:71]
	v_mov_b32_e32 v72, v68
	v_mov_b32_e32 v73, v66
	v_mov_b32_e32 v66, v69
	v_pk_add_f32 v[66:67], v[72:73], v[66:67]
	v_add_f32_e32 v68, v70, v71
	v_add_f32_e32 v67, v67, v68
	v_add_f32_e32 v66, v66, v67
	ds_bpermute_b32 v67, v155, v66
	v_cmp_lt_i32_e32 vcc, v157, v154
	s_waitcnt lgkmcnt(0)
	v_add_f32_e32 v66, v66, v67
	v_cndmask_b32_e32 v67, v229, v157, vcc
	v_lshlrev_b32_e32 v67, 2, v67
	ds_bpermute_b32 v67, v67, v66
	s_waitcnt lgkmcnt(0)
	v_add_f32_e32 v66, v66, v67
	v_max_f32_e32 v67, v153, v153
	v_max_f32_e32 v153, v67, v66
.LBB0_202:
	v_lshlrev_b64 v[68:69], 8, v[144:145]
	v_lshl_add_u64 v[68:69], s[22:23], 0, v[68:69]
	v_lshl_add_u64 v[68:69], v[68:69], 0, v[0:1]
	v_cndmask_b32_e64 v66, v161, v162, s[40:41]
	v_add_co_u32_e32 v74, vcc, 0x8000, v68
	v_pk_mul_f32 v[64:65], v[64:65], v[66:67] op_sel_hi:[1,0]
	v_pk_mul_f32 v[62:63], v[62:63], v[66:67] op_sel_hi:[1,0]
	v_pk_mul_f32 v[60:61], v[60:61], v[66:67] op_sel_hi:[1,0]
	v_pk_mul_f32 v[58:59], v[58:59], v[66:67] op_sel_hi:[1,0]
	v_addc_co_u32_e32 v75, vcc, 0, v69, vcc
	v_cvt_pk_bf16_f32 v70, v62, v63
	v_cvt_pk_bf16_f32 v71, v64, v65
	v_cvt_pk_bf16_f32 v72, v58, v59
	v_cvt_pk_bf16_f32 v73, v60, v61
	s_and_b64 vcc, exec, s[48:49]
	global_store_dwordx4 v[74:75], v[70:73], off nt
	s_cbranch_vccnz .LBB0_204
	v_pk_mul_f32 v[64:65], v[64:65], v[64:65]
	v_pk_mul_f32 v[62:63], v[62:63], v[62:63]
	v_pk_mul_f32 v[60:61], v[60:61], v[60:61]
	v_pk_mov_b32 v[70:71], v[62:63], v[64:65] op_sel:[1,0]
	v_mov_b32_e32 v63, v65
	v_pk_mul_f32 v[58:59], v[58:59], v[58:59]
	v_pk_add_f32 v[62:63], v[70:71], v[62:63]
	v_mov_b32_e32 v64, v60
	v_mov_b32_e32 v65, v58
	v_mov_b32_e32 v58, v61
	v_pk_add_f32 v[58:59], v[64:65], v[58:59]
	v_add_f32_e32 v60, v62, v63
	v_add_f32_e32 v59, v59, v60
	v_add_f32_e32 v58, v58, v59
	ds_bpermute_b32 v59, v155, v58
	v_cmp_lt_i32_e32 vcc, v157, v154
	s_waitcnt lgkmcnt(0)
	v_add_f32_e32 v58, v58, v59
	v_cndmask_b32_e32 v59, v229, v157, vcc
	v_lshlrev_b32_e32 v59, 2, v59
	ds_bpermute_b32 v59, v59, v58
	s_waitcnt lgkmcnt(0)
	v_add_f32_e32 v58, v58, v59
	v_max_f32_e32 v59, v159, v159
	v_max_f32_e32 v159, v59, v58
.LBB0_204:
	s_mov_b64 s[50:51], 0x8000
	v_lshl_add_u64 v[62:63], v[68:69], 0, s[50:51]
	v_mov_b32_e32 v67, v66
	v_mov_b32_e32 v58, v66
	v_mov_b32_e32 v59, v66
	v_add_co_u32_e32 v62, vcc, 0x600000, v62
	v_pk_mul_f32 v[56:57], v[56:57], v[58:59]
	v_pk_mul_f32 v[54:55], v[54:55], v[66:67]
	v_pk_mul_f32 v[52:53], v[52:53], v[58:59]
	v_pk_mul_f32 v[50:51], v[50:51], v[66:67]
	v_addc_co_u32_e32 v63, vcc, 0, v63, vcc
	v_cvt_pk_bf16_f32 v58, v54, v55
	v_cvt_pk_bf16_f32 v59, v56, v57
	v_cvt_pk_bf16_f32 v60, v50, v51
	v_cvt_pk_bf16_f32 v61, v52, v53
	s_and_b64 vcc, exec, s[48:49]
	global_store_dwordx4 v[62:63], v[58:61], off nt
	s_cbranch_vccnz .LBB0_206
	v_pk_mul_f32 v[56:57], v[56:57], v[56:57]
	v_pk_mul_f32 v[54:55], v[54:55], v[54:55]
	v_pk_mul_f32 v[52:53], v[52:53], v[52:53]
	v_pk_mov_b32 v[58:59], v[54:55], v[56:57] op_sel:[1,0]
	v_mov_b32_e32 v55, v57
	v_pk_mul_f32 v[50:51], v[50:51], v[50:51]
	v_pk_add_f32 v[54:55], v[58:59], v[54:55]
	v_mov_b32_e32 v56, v52
	v_mov_b32_e32 v57, v50
	v_mov_b32_e32 v50, v53
	v_pk_add_f32 v[50:51], v[56:57], v[50:51]
	v_add_f32_e32 v52, v54, v55
	v_add_f32_e32 v51, v51, v52
	v_add_f32_e32 v50, v50, v51
	ds_bpermute_b32 v51, v155, v50
	v_cmp_lt_i32_e32 vcc, v157, v154
	s_waitcnt lgkmcnt(0)
	v_add_f32_e32 v50, v50, v51
	v_cndmask_b32_e32 v51, v229, v157, vcc
	v_lshlrev_b32_e32 v51, 2, v51
	ds_bpermute_b32 v51, v51, v50
	s_waitcnt lgkmcnt(0)
	v_add_f32_e32 v50, v50, v51
	v_max_f32_e32 v51, v153, v153
	v_max_f32_e32 v153, v51, v50
.LBB0_206:
	v_lshlrev_b64 v[52:53], 8, v[144:145]
	v_lshl_add_u64 v[52:53], s[22:23], 0, v[52:53]
	v_lshl_add_u64 v[52:53], v[52:53], 0, v[0:1]
	v_cndmask_b32_e64 v50, v119, v118, s[40:41]
	v_add_co_u32_e32 v58, vcc, 0x9000, v52
	v_pk_mul_f32 v[48:49], v[48:49], v[50:51] op_sel_hi:[1,0]
	v_pk_mul_f32 v[46:47], v[46:47], v[50:51] op_sel_hi:[1,0]
	v_pk_mul_f32 v[44:45], v[44:45], v[50:51] op_sel_hi:[1,0]
	v_pk_mul_f32 v[42:43], v[42:43], v[50:51] op_sel_hi:[1,0]
	v_addc_co_u32_e32 v59, vcc, 0, v53, vcc
	v_cvt_pk_bf16_f32 v54, v46, v47
	v_cvt_pk_bf16_f32 v55, v48, v49
	v_cvt_pk_bf16_f32 v56, v42, v43
	v_cvt_pk_bf16_f32 v57, v44, v45
	s_and_b64 vcc, exec, s[48:49]
	global_store_dwordx4 v[58:59], v[54:57], off nt
	s_cbranch_vccnz .LBB0_208
	v_pk_mul_f32 v[48:49], v[48:49], v[48:49]
	v_pk_mul_f32 v[46:47], v[46:47], v[46:47]
	v_pk_mul_f32 v[44:45], v[44:45], v[44:45]
	v_pk_mov_b32 v[54:55], v[46:47], v[48:49] op_sel:[1,0]
	v_mov_b32_e32 v47, v49
	v_pk_mul_f32 v[42:43], v[42:43], v[42:43]
	v_pk_add_f32 v[46:47], v[54:55], v[46:47]
	v_mov_b32_e32 v48, v44
	v_mov_b32_e32 v49, v42
	v_mov_b32_e32 v42, v45
	v_pk_add_f32 v[42:43], v[48:49], v[42:43]
	v_add_f32_e32 v44, v46, v47
	v_add_f32_e32 v43, v43, v44
	v_add_f32_e32 v42, v42, v43
	ds_bpermute_b32 v43, v155, v42
	v_cmp_lt_i32_e32 vcc, v157, v154
	s_waitcnt lgkmcnt(0)
	v_add_f32_e32 v42, v42, v43
	v_cndmask_b32_e32 v43, v229, v157, vcc
	v_lshlrev_b32_e32 v43, 2, v43
	ds_bpermute_b32 v43, v43, v42
	s_waitcnt lgkmcnt(0)
	v_add_f32_e32 v42, v42, v43
	v_max_f32_e32 v43, v159, v159
	v_max_f32_e32 v159, v43, v42
.LBB0_208:
	s_mov_b64 s[50:51], 0x9000
	v_lshl_add_u64 v[46:47], v[52:53], 0, s[50:51]
	v_mov_b32_e32 v51, v50
	v_mov_b32_e32 v42, v50
	v_mov_b32_e32 v43, v50
	v_add_co_u32_e32 v46, vcc, 0x600000, v46
	v_pk_mul_f32 v[40:41], v[40:41], v[42:43]
	v_pk_mul_f32 v[38:39], v[38:39], v[50:51]
	v_pk_mul_f32 v[36:37], v[36:37], v[42:43]
	v_pk_mul_f32 v[34:35], v[34:35], v[50:51]
	v_addc_co_u32_e32 v47, vcc, 0, v47, vcc
	v_cvt_pk_bf16_f32 v42, v38, v39
	v_cvt_pk_bf16_f32 v43, v40, v41
	v_cvt_pk_bf16_f32 v44, v34, v35
	v_cvt_pk_bf16_f32 v45, v36, v37
	s_and_b64 vcc, exec, s[48:49]
	global_store_dwordx4 v[46:47], v[42:45], off nt
	s_cbranch_vccnz .LBB0_210
	v_pk_mul_f32 v[40:41], v[40:41], v[40:41]
	v_pk_mul_f32 v[38:39], v[38:39], v[38:39]
	v_pk_mul_f32 v[36:37], v[36:37], v[36:37]
	v_pk_mov_b32 v[42:43], v[38:39], v[40:41] op_sel:[1,0]
	v_mov_b32_e32 v39, v41
	v_pk_mul_f32 v[34:35], v[34:35], v[34:35]
	v_pk_add_f32 v[38:39], v[42:43], v[38:39]
	v_mov_b32_e32 v40, v36
	v_mov_b32_e32 v41, v34
	v_mov_b32_e32 v34, v37
	v_pk_add_f32 v[34:35], v[40:41], v[34:35]
	v_add_f32_e32 v36, v38, v39
	v_add_f32_e32 v35, v35, v36
	v_add_f32_e32 v34, v34, v35
	ds_bpermute_b32 v35, v155, v34
	v_cmp_lt_i32_e32 vcc, v157, v154
	s_waitcnt lgkmcnt(0)
	v_add_f32_e32 v34, v34, v35
	v_cndmask_b32_e32 v35, v229, v157, vcc
	v_lshlrev_b32_e32 v35, 2, v35
	ds_bpermute_b32 v35, v35, v34
	s_waitcnt lgkmcnt(0)
	v_add_f32_e32 v34, v34, v35
	v_max_f32_e32 v35, v153, v153
	v_max_f32_e32 v153, v35, v34
.LBB0_210:
	v_lshlrev_b64 v[36:37], 8, v[144:145]
	v_lshl_add_u64 v[36:37], s[22:23], 0, v[36:37]
	v_lshl_add_u64 v[36:37], v[36:37], 0, v[0:1]
	v_cndmask_b32_e64 v34, v103, v102, s[40:41]
	v_add_co_u32_e32 v42, vcc, 0xa000, v36
	v_pk_mul_f32 v[32:33], v[32:33], v[34:35] op_sel_hi:[1,0]
	v_pk_mul_f32 v[30:31], v[30:31], v[34:35] op_sel_hi:[1,0]
	v_pk_mul_f32 v[28:29], v[28:29], v[34:35] op_sel_hi:[1,0]
	v_pk_mul_f32 v[26:27], v[26:27], v[34:35] op_sel_hi:[1,0]
	v_addc_co_u32_e32 v43, vcc, 0, v37, vcc
	v_cvt_pk_bf16_f32 v38, v30, v31
	v_cvt_pk_bf16_f32 v39, v32, v33
	v_cvt_pk_bf16_f32 v40, v26, v27
	v_cvt_pk_bf16_f32 v41, v28, v29
	s_and_b64 vcc, exec, s[48:49]
	global_store_dwordx4 v[42:43], v[38:41], off nt
	s_cbranch_vccnz .LBB0_212
	v_pk_mul_f32 v[32:33], v[32:33], v[32:33]
	v_pk_mul_f32 v[30:31], v[30:31], v[30:31]
	v_pk_mul_f32 v[28:29], v[28:29], v[28:29]
	v_pk_mov_b32 v[38:39], v[30:31], v[32:33] op_sel:[1,0]
	v_mov_b32_e32 v31, v33
	v_pk_mul_f32 v[26:27], v[26:27], v[26:27]
	v_pk_add_f32 v[30:31], v[38:39], v[30:31]
	v_mov_b32_e32 v32, v28
	v_mov_b32_e32 v33, v26
	v_mov_b32_e32 v26, v29
	v_pk_add_f32 v[26:27], v[32:33], v[26:27]
	v_add_f32_e32 v28, v30, v31
	v_add_f32_e32 v27, v27, v28
	v_add_f32_e32 v26, v26, v27
	ds_bpermute_b32 v27, v155, v26
	v_cmp_lt_i32_e32 vcc, v157, v154
	s_waitcnt lgkmcnt(0)
	v_add_f32_e32 v26, v26, v27
	v_cndmask_b32_e32 v27, v229, v157, vcc
	v_lshlrev_b32_e32 v27, 2, v27
	ds_bpermute_b32 v27, v27, v26
	s_waitcnt lgkmcnt(0)
	v_add_f32_e32 v26, v26, v27
	v_max_f32_e32 v27, v159, v159
	v_max_f32_e32 v159, v27, v26
.LBB0_212:
	s_mov_b64 s[50:51], 0xa000
	v_lshl_add_u64 v[30:31], v[36:37], 0, s[50:51]
	v_mov_b32_e32 v35, v34
	v_mov_b32_e32 v26, v34
	v_mov_b32_e32 v27, v34
	v_add_co_u32_e32 v30, vcc, 0x600000, v30
	v_pk_mul_f32 v[24:25], v[24:25], v[26:27]
	v_pk_mul_f32 v[22:23], v[22:23], v[34:35]
	v_pk_mul_f32 v[20:21], v[20:21], v[26:27]
	v_pk_mul_f32 v[18:19], v[18:19], v[34:35]
	v_addc_co_u32_e32 v31, vcc, 0, v31, vcc
	v_cvt_pk_bf16_f32 v26, v22, v23
	v_cvt_pk_bf16_f32 v27, v24, v25
	v_cvt_pk_bf16_f32 v28, v18, v19
	v_cvt_pk_bf16_f32 v29, v20, v21
	s_and_b64 vcc, exec, s[48:49]
	global_store_dwordx4 v[30:31], v[26:29], off nt
	s_cbranch_vccnz .LBB0_214
	v_pk_mul_f32 v[24:25], v[24:25], v[24:25]
	v_pk_mul_f32 v[22:23], v[22:23], v[22:23]
	v_pk_mul_f32 v[20:21], v[20:21], v[20:21]
	v_pk_mov_b32 v[26:27], v[22:23], v[24:25] op_sel:[1,0]
	v_mov_b32_e32 v23, v25
	v_pk_mul_f32 v[18:19], v[18:19], v[18:19]
	v_pk_add_f32 v[22:23], v[26:27], v[22:23]
	v_mov_b32_e32 v24, v20
	v_mov_b32_e32 v25, v18
	v_mov_b32_e32 v18, v21
	v_pk_add_f32 v[18:19], v[24:25], v[18:19]
	v_add_f32_e32 v20, v22, v23
	v_add_f32_e32 v19, v19, v20
	v_add_f32_e32 v18, v18, v19
	ds_bpermute_b32 v19, v155, v18
	v_cmp_lt_i32_e32 vcc, v157, v154
	s_waitcnt lgkmcnt(0)
	v_add_f32_e32 v18, v18, v19
	v_cndmask_b32_e32 v19, v229, v157, vcc
	v_lshlrev_b32_e32 v19, 2, v19
	ds_bpermute_b32 v19, v19, v18
	s_waitcnt lgkmcnt(0)
	v_add_f32_e32 v18, v18, v19
	v_max_f32_e32 v19, v153, v153
	v_max_f32_e32 v153, v19, v18
.LBB0_214:
	v_lshlrev_b64 v[20:21], 8, v[144:145]
	v_lshl_add_u64 v[20:21], s[22:23], 0, v[20:21]
	v_lshl_add_u64 v[20:21], v[20:21], 0, v[0:1]
	v_cndmask_b32_e64 v18, v87, v86, s[40:41]
	v_add_co_u32_e32 v26, vcc, 0xb000, v20
	v_pk_mul_f32 v[16:17], v[16:17], v[18:19] op_sel_hi:[1,0]
	v_pk_mul_f32 v[14:15], v[14:15], v[18:19] op_sel_hi:[1,0]
	v_pk_mul_f32 v[12:13], v[12:13], v[18:19] op_sel_hi:[1,0]
	v_pk_mul_f32 v[10:11], v[10:11], v[18:19] op_sel_hi:[1,0]
	v_addc_co_u32_e32 v27, vcc, 0, v21, vcc
	v_cvt_pk_bf16_f32 v22, v14, v15
	v_cvt_pk_bf16_f32 v23, v16, v17
	v_cvt_pk_bf16_f32 v24, v10, v11
	v_cvt_pk_bf16_f32 v25, v12, v13
	s_and_b64 vcc, exec, s[48:49]
	global_store_dwordx4 v[26:27], v[22:25], off nt
	s_cbranch_vccnz .LBB0_216
	v_pk_mul_f32 v[16:17], v[16:17], v[16:17]
	v_pk_mul_f32 v[14:15], v[14:15], v[14:15]
	v_pk_mul_f32 v[12:13], v[12:13], v[12:13]
	v_pk_mov_b32 v[22:23], v[14:15], v[16:17] op_sel:[1,0]
	v_mov_b32_e32 v15, v17
	v_pk_mul_f32 v[10:11], v[10:11], v[10:11]
	v_pk_add_f32 v[14:15], v[22:23], v[14:15]
	v_mov_b32_e32 v16, v12
	v_mov_b32_e32 v17, v10
	v_mov_b32_e32 v10, v13
	v_pk_add_f32 v[10:11], v[16:17], v[10:11]
	v_add_f32_e32 v0, v14, v15
	v_add_f32_e32 v0, v11, v0
	v_add_f32_e32 v0, v10, v0
	ds_bpermute_b32 v10, v155, v0
	v_cmp_lt_i32_e32 vcc, v157, v154
	s_waitcnt lgkmcnt(0)
	v_add_f32_e32 v0, v0, v10
	v_cndmask_b32_e32 v10, v229, v157, vcc
	v_lshlrev_b32_e32 v10, 2, v10
	ds_bpermute_b32 v10, v10, v0
	s_waitcnt lgkmcnt(0)
	v_add_f32_e32 v0, v0, v10
	v_max_f32_e32 v10, v159, v159
	v_max_f32_e32 v159, v10, v0
.LBB0_216:
	s_mov_b64 s[22:23], 0xb000
	v_lshl_add_u64 v[14:15], v[20:21], 0, s[22:23]
	v_mov_b32_e32 v19, v18
	v_mov_b32_e32 v10, v18
	v_mov_b32_e32 v11, v18
	v_add_co_u32_e32 v14, vcc, 0x600000, v14
	v_pk_mul_f32 v[8:9], v[8:9], v[10:11]
	v_pk_mul_f32 v[6:7], v[6:7], v[18:19]
	v_pk_mul_f32 v[4:5], v[4:5], v[10:11]
	v_pk_mul_f32 v[2:3], v[2:3], v[18:19]
	v_addc_co_u32_e32 v15, vcc, 0, v15, vcc
	v_cvt_pk_bf16_f32 v10, v6, v7
	v_cvt_pk_bf16_f32 v11, v8, v9
	v_cvt_pk_bf16_f32 v12, v2, v3
	v_cvt_pk_bf16_f32 v13, v4, v5
	s_and_b64 vcc, exec, s[48:49]
	global_store_dwordx4 v[14:15], v[10:13], off nt
	s_cbranch_vccnz .LBB0_227
	v_mul_f32_e32 v0, v7, v7
	v_fmac_f32_e32 v0, v6, v6
	v_mul_f32_e32 v6, v9, v9
	v_fmac_f32_e32 v6, v8, v8
	v_mul_f32_e32 v3, v3, v3
	v_add_f32_e32 v0, v0, v6
	v_fmac_f32_e32 v3, v2, v2
	v_mul_f32_e32 v2, v5, v5
	v_add_f32_e32 v0, v3, v0
	v_fmac_f32_e32 v2, v4, v4
	v_add_f32_e32 v0, v2, v0
	ds_bpermute_b32 v2, v155, v0
	v_cmp_lt_i32_e32 vcc, v157, v154
	v_max_f32_e32 v4, v153, v153
	s_waitcnt lgkmcnt(0)
	v_add_f32_e32 v0, v0, v2
	v_cndmask_b32_e32 v2, v229, v157, vcc
	v_lshlrev_b32_e32 v2, 2, v2
	ds_bpermute_b32 v2, v2, v0
	s_waitcnt lgkmcnt(0)
	v_add_f32_e32 v0, v0, v2
	v_xor_b32_e32 v2, 1, v229
	v_cmp_lt_i32_e32 vcc, v2, v154
	v_max_f32_e32 v0, v4, v0
	v_max_f32_e32 v4, v159, v159
	v_cndmask_b32_e32 v2, v229, v2, vcc
	v_lshlrev_b32_e32 v2, 2, v2
	ds_bpermute_b32 v3, v2, v159
	ds_bpermute_b32 v2, v2, v0
	s_waitcnt lgkmcnt(1)
	v_max_f32_e32 v3, v3, v3
	v_max_f32_e32 v3, v4, v3
	v_xor_b32_e32 v4, 2, v229
	v_cmp_lt_i32_e32 vcc, v4, v154
	s_waitcnt lgkmcnt(0)
	v_max_f32_e32 v2, v2, v2
	v_max_f32_e32 v0, v0, v2
	v_cndmask_b32_e32 v4, v229, v4, vcc
	v_lshlrev_b32_e32 v4, 2, v4
	ds_bpermute_b32 v5, v4, v3
	ds_bpermute_b32 v2, v4, v0
	s_waitcnt lgkmcnt(1)
	v_max_f32_e32 v4, v5, v5
	v_max_f32_e32 v3, v3, v4
	v_xor_b32_e32 v4, 4, v229
	v_cmp_lt_i32_e32 vcc, v4, v154
	s_waitcnt lgkmcnt(0)
	v_max_f32_e32 v2, v2, v2
	v_max_f32_e32 v0, v0, v2
	v_cndmask_b32_e32 v4, v229, v4, vcc
	v_lshlrev_b32_e32 v4, 2, v4
	ds_bpermute_b32 v2, v4, v0
	ds_bpermute_b32 v5, v4, v3
	s_waitcnt lgkmcnt(1)
	v_max_f32_e32 v2, v2, v2
	v_max_f32_e32 v0, v0, v2
	v_xor_b32_e32 v2, 8, v229
	v_cmp_lt_i32_e32 vcc, v2, v154
	s_waitcnt lgkmcnt(0)
	v_max_f32_e32 v4, v5, v5
	v_max_f32_e32 v3, v3, v4
	v_cndmask_b32_e32 v2, v229, v2, vcc
	v_lshlrev_b32_e32 v2, 2, v2
	ds_bpermute_b32 v4, v2, v3
	ds_bpermute_b32 v2, v2, v0
	s_and_saveexec_b64 s[22:23], s[44:45]
	s_cbranch_execz .LBB0_226
	s_waitcnt lgkmcnt(1)
	v_max_f32_e32 v4, v4, v4
	v_max_f32_e32 v3, v3, v3
	s_mov_b64 s[48:49], exec
	v_max_f32_e32 v3, v3, v4
	s_mov_b32 s15, 0
